# attn loop 2nd-half vmcnt ladder 2/1/0 -> vmcnt(3) except last iteration
# speedup vs baseline: 1.0001x; 1.0001x over previous
.LBB0_403:
	v_add_f32_e32 v178, v179, v178
	ds_read_b64_tr_b16 v[182:183], v202 offset:0
	ds_read_b64_tr_b16 v[184:185], v202 offset:0x800
	ds_read_b64_tr_b16 v[186:187], v202 offset:0x200
	ds_read_b64_tr_b16 v[188:189], v202 offset:0xa00
	ds_read_b64_tr_b16 v[214:215], v202 offset:0x400
	ds_read_b64_tr_b16 v[216:217], v202 offset:0xc00
	ds_read_b64_tr_b16 v[218:219], v202 offset:0x600
	ds_read_b64_tr_b16 v[220:221], v202 offset:0xe00
	ds_read_b64_tr_b16 v[222:223], v202 offset:0x1000
	ds_read_b64_tr_b16 v[224:225], v202 offset:0x1800
	ds_read_b64_tr_b16 v[226:227], v202 offset:0x1200
	ds_read_b64_tr_b16 v[228:229], v202 offset:0x1a00
	ds_read_b64_tr_b16 v[230:231], v202 offset:0x1400
	ds_read_b64_tr_b16 v[232:233], v202 offset:0x1c00
	ds_read_b64_tr_b16 v[234:235], v202 offset:0x1600
	ds_read_b64_tr_b16 v[236:237], v202 offset:0x1e00
	s_nop 0
	s_waitcnt lgkmcnt(8)
	v_exp_f32_e32 v112, v112
	v_mfma_f32_32x32x16_bf16 v[0:15], v[144:147], v[182:185], v[0:15]
	v_exp_f32_e32 v113, v113
	v_exp_f32_e32 v114, v114
	v_exp_f32_e32 v115, v115
	v_exp_f32_e32 v116, v116
	v_exp_f32_e32 v117, v117
	v_exp_f32_e32 v118, v118
	v_exp_f32_e32 v119, v119
	v_mfma_f32_32x32x16_bf16 v[48:63], v[144:147], v[186:189], v[48:63]
	v_exp_f32_e32 v120, v120
	v_exp_f32_e32 v121, v121
	v_exp_f32_e32 v122, v122
	v_exp_f32_e32 v123, v123
	v_exp_f32_e32 v124, v124
	v_exp_f32_e32 v125, v125
	v_exp_f32_e32 v126, v126
	v_mfma_f32_32x32x16_bf16 v[32:47], v[144:147], v[214:217], v[32:47]
	v_exp_f32_e32 v127, v127
	s_addk_i32 s51, 0x80
	s_add_i32 s50, s50, 2
	s_and_b64 vcc, exec, s[8:9]
	v_mfma_f32_32x32x16_bf16 v[16:31], v[144:147], v[218:221], v[16:31]
	ds_read_b64_tr_b16 v[144:145], v202 offset:0x2000
	ds_read_b64_tr_b16 v[146:147], v202 offset:0x2800
	ds_read_b64_tr_b16 v[182:183], v202 offset:0x2200
	ds_read_b64_tr_b16 v[184:185], v202 offset:0x2a00
	ds_read_b64_tr_b16 v[186:187], v202 offset:0x2400
	ds_read_b64_tr_b16 v[188:189], v202 offset:0x2c00
	ds_read_b64_tr_b16 v[214:215], v202 offset:0x2600
	ds_read_b64_tr_b16 v[216:217], v202 offset:0x2e00
	s_waitcnt lgkmcnt(8)
	ds_read_b64_tr_b16 v[218:219], v202 offset:0x3000
	ds_read_b64_tr_b16 v[220:221], v202 offset:0x3800
	s_nop 0
	v_mfma_f32_32x32x16_bf16 v[0:15], v[140:143], v[222:225], v[0:15]
	ds_read_b64_tr_b16 v[222:223], v202 offset:0x3200
	ds_read_b64_tr_b16 v[224:225], v202 offset:0x3a00
	v_mfma_f32_32x32x16_bf16 v[48:63], v[140:143], v[226:229], v[48:63]
	ds_read_b64_tr_b16 v[226:227], v202 offset:0x3400
	ds_read_b64_tr_b16 v[228:229], v202 offset:0x3c00
	v_mfma_f32_32x32x16_bf16 v[32:47], v[140:143], v[230:233], v[32:47]
	ds_read_b64_tr_b16 v[230:231], v202 offset:0x3600
	ds_read_b64_tr_b16 v[232:233], v202 offset:0x3e00
	s_waitcnt lgkmcnt(8)
	s_nop 0
	s_waitcnt lgkmcnt(0)
	v_mfma_f32_32x32x16_bf16 v[16:31], v[140:143], v[234:237], v[16:31]
	v_add_f32_e32 v140, 0, v112
	v_add_f32_e32 v140, v113, v140
	v_add_f32_e32 v140, v114, v140
	v_add_f32_e32 v140, v115, v140
	v_add_f32_e32 v140, v116, v140
	v_add_f32_e32 v140, v117, v140
	v_add_f32_e32 v140, v118, v140
	v_mfma_f32_32x32x16_bf16 v[0:15], v[164:167], v[144:147], v[0:15]
	v_add_f32_e32 v140, v119, v140
	v_add_f32_e32 v140, v120, v140
	v_add_f32_e32 v140, v121, v140
	v_add_f32_e32 v140, v122, v140
	v_add_f32_e32 v140, v123, v140
	v_add_f32_e32 v140, v124, v140
	v_add_f32_e32 v140, v125, v140
	v_mfma_f32_32x32x16_bf16 v[48:63], v[164:167], v[182:185], v[48:63]
	v_add_f32_e32 v140, v126, v140
	v_cvt_pk_bf16_f32 v144, v112, v113
	v_cvt_pk_bf16_f32 v145, v114, v115
	v_cvt_pk_bf16_f32 v146, v116, v117
	v_cvt_pk_bf16_f32 v147, v118, v119
	v_mfma_f32_32x32x16_bf16 v[32:47], v[164:167], v[186:189], v[32:47]
	v_mfma_f32_32x32x16_bf16 v[16:31], v[164:167], v[214:217], v[16:31]
	v_add_f32_e32 v164, v127, v140
	v_cvt_pk_bf16_f32 v140, v120, v121
	v_cvt_pk_bf16_f32 v141, v122, v123
	v_cvt_pk_bf16_f32 v142, v124, v125
	v_cvt_pk_bf16_f32 v143, v126, v127
	s_barrier
	v_mfma_f32_32x32x16_bf16 v[0:15], v[160:163], v[218:221], v[0:15]
	s_waitcnt vmcnt(3)
	s_cbranch_vccz .Lattn_w3
	s_waitcnt vmcnt(0)
.Lattn_w3:
	ds_write_b128 v205, v[148:151] offset:16384
	ds_write_b128 v206, v[152:155] offset:16384
	ds_write_b128 v207, v[156:159] offset:40960
	s_waitcnt lgkmcnt(0)
	s_barrier
	v_mfma_f32_32x32x16_bf16 v[48:63], v[160:163], v[222:225], v[48:63]
	v_mfma_f32_32x32x16_bf16 v[32:47], v[160:163], v[226:229], v[32:47]
	v_mfma_f32_32x32x16_bf16 v[16:31], v[160:163], v[230:233], v[16:31]
	s_cbranch_vccnz .LBB0_411
	s_mov_b64 s[8:9], s[6:7]
	s_branch .LBB0_398
